# FFN epilogue conv section: channel-half outer loop, taps read from LDS once per half instead of per (row-half, channel-half)
# baseline (speedup 1.0000x reference)
; #define LAS __attribute__((address_space(3)))
;     __device__ __forceinline__ void operator()(f32x4 (&acc)[2][2][4][2], const Unit& u, int wr, int wc, int fr, int fq, int next_pn) const {
;     ...
;                 if (sl > 0) { const LAS float* hp = H + ((sl - 1) * 2) * 256 + tcol + 4 * hf; hg62 = *(const LAS f32x4*)hp; hv62 = *(const LAS f32x4*)(hp + 128); hg63 = *(const LAS f32x4*)(hp + 256); hv63 = *(const LAS f32x4*)(hp + 384); }
;                 f32x4 sg3, sg2, sv3, sv2;
; #pragma unroll
;                 for (int j = 0; j < 4; ++j) { sg3[j] = dpp_shr1(hg63[j], acc[ai][0][3][hf][j]); sg2[j] = dpp_shr1(hg62[j], acc[ai][0][2][hf][j]); sv3[j] = dpp_shr1(hv63[j], acc[ai][1][3][hf][j]); sv2[j] = dpp_shr1(hv62[j], acc[ai][1][2][hf][j]); }
; #pragma unroll
;                 for (int m = 0; m < 4; ++m) {
;                     const f32x4 cg = acc[ai][0][m][hf], cv = acc[ai][1][m][hf];
;                     const f32x4 g1v = (m == 0) ? sg3 : acc[ai][0][m == 0 ? 0 : m - 1][hf], g2v = (m == 0) ? sg2 : (m == 1) ? sg3 : acc[ai][0][m < 2 ? 0 : m - 2][hf];
;                     const f32x4 v1v = (m == 0) ? sv3 : acc[ai][1][m == 0 ? 0 : m - 1][hf], v2v = (m == 0) ? sv2 : (m == 1) ? sv3 : acc[ai][1][m < 2 ? 0 : m - 2][hf];
;                     float o[4];
; #pragma unroll
;                     for (int j2 = 0; j2 < 2; ++j2) {
;                         const int j = 2 * j2;
;                         const f32x2v g1 = {g1v[j], g1v[j + 1]}, g2 = {g2v[j], g2v[j + 1]}, v1 = {v1v[j], v1v[j + 1]}, v2 = {v2v[j], v2v[j + 1]};
;                         const f32x2v c_g = {cg[j], cg[j + 1]}, c_v = {cv[j], cv[j + 1]};
;                         const f32x2v gc = (f32x2v){wg0[j], wg0[j + 1]} * g2 + ((f32x2v){wg1[j], wg1[j + 1]} * g1 + ((f32x2v){wg2[j], wg2[j + 1]} * c_g + (f32x2v){bg[j], bg[j + 1]}));
;                         const f32x2v vc = (f32x2v){wv0[j], wv0[j + 1]} * v2 + ((f32x2v){wv1[j], wv1[j + 1]} * v1 + ((f32x2v){wv2[j], wv2[j + 1]} * c_v + (f32x2v){bvv[j], bvv[j + 1]}));
;                         const f32x2v e = gc * (-1.4426950408889634f); f32x2v t; t.x = __builtin_amdgcn_exp2f(e.x); t.y = __builtin_amdgcn_exp2f(e.y);
;                         const f32x2v d = t + 1.0f; f32x2v r; r.x = __builtin_amdgcn_rcpf(d.x); r.y = __builtin_amdgcn_rcpf(d.y);
;                         const f32x2v oo = (gc * r) * vc; o[j] = oo.x; o[j + 1] = oo.y; }
.Lffn_hj_1:
	s_waitcnt lgkmcnt(0)
	v_mov_b32_dpp v170, v126 row_shr:1 row_mask:0xf bank_mask:0xf
	v_mov_b32_dpp v162, v114 row_shr:1 row_mask:0xf bank_mask:0xf
	v_mov_b32_dpp v174, v122 row_shr:1 row_mask:0xf bank_mask:0xf
	v_mov_b32_dpp v166, v118 row_shr:1 row_mask:0xf bank_mask:0xf
	v_mov_b32_dpp v171, v127 row_shr:1 row_mask:0xf bank_mask:0xf
	v_mov_b32_dpp v163, v115 row_shr:1 row_mask:0xf bank_mask:0xf
	v_mov_b32_dpp v175, v123 row_shr:1 row_mask:0xf bank_mask:0xf
	v_mov_b32_dpp v167, v119 row_shr:1 row_mask:0xf bank_mask:0xf
	v_mov_b32_dpp v172, v128 row_shr:1 row_mask:0xf bank_mask:0xf
	v_mov_b32_dpp v164, v116 row_shr:1 row_mask:0xf bank_mask:0xf
	v_mov_b32_dpp v176, v124 row_shr:1 row_mask:0xf bank_mask:0xf
	v_mov_b32_dpp v168, v120 row_shr:1 row_mask:0xf bank_mask:0xf
	v_mov_b32_dpp v173, v129 row_shr:1 row_mask:0xf bank_mask:0xf
	v_mov_b32_dpp v165, v117 row_shr:1 row_mask:0xf bank_mask:0xf
	v_mov_b32_dpp v177, v125 row_shr:1 row_mask:0xf bank_mask:0xf
	v_mov_b32_dpp v169, v121 row_shr:1 row_mask:0xf bank_mask:0xf
	v_pk_fma_f32 v[214:215], v[110:111], v[146:147], v[154:155]
	v_pk_fma_f32 v[220:221], v[112:113], v[148:149], v[156:157]
	v_pk_fma_f32 v[216:217], v[102:103], v[150:151], v[158:159]
	v_pk_fma_f32 v[222:223], v[104:105], v[152:153], v[160:161]
	v_pk_fma_f32 v[214:215], v[138:139], v[170:171], v[214:215]
	v_pk_fma_f32 v[220:221], v[140:141], v[172:173], v[220:221]
	v_pk_fma_f32 v[216:217], v[142:143], v[174:175], v[216:217]
	v_pk_fma_f32 v[222:223], v[144:145], v[176:177], v[222:223]
	v_pk_fma_f32 v[214:215], v[130:131], v[162:163], v[214:215]
	v_pk_fma_f32 v[220:221], v[132:133], v[164:165], v[220:221]
	v_pk_fma_f32 v[216:217], v[134:135], v[166:167], v[216:217]
	v_pk_fma_f32 v[222:223], v[136:137], v[168:169], v[222:223]
	v_pk_mul_f32 v[218:219], v[214:215], s[88:89] op_sel_hi:[1,0]
	v_pk_mul_f32 v[224:225], v[220:221], s[88:89] op_sel_hi:[1,0]
	v_exp_f32_e32 v218, v218
	v_exp_f32_e32 v224, v224
	v_exp_f32_e32 v219, v219
	v_exp_f32_e32 v225, v225
	v_pk_add_f32 v[218:219], v[218:219], 1.0 op_sel_hi:[1,0]
	v_pk_add_f32 v[224:225], v[224:225], 1.0 op_sel_hi:[1,0]
	v_rcp_f32_e32 v218, v218
	v_rcp_f32_e32 v224, v224
	v_rcp_f32_e32 v219, v219
	v_rcp_f32_e32 v225, v225
	v_pk_mul_f32 v[214:215], v[214:215], v[218:219]
	v_pk_mul_f32 v[220:221], v[220:221], v[224:225]
	v_pk_mul_f32 v[214:215], v[216:217], v[214:215]
	v_pk_mul_f32 v[220:221], v[222:223], v[220:221]
	v_cvt_pk_bf16_f32 v226, v214, v215
	v_cvt_pk_bf16_f32 v227, v220, v221
	v_pk_fma_f32 v[214:215], v[94:95], v[146:147], v[154:155]
	v_pk_fma_f32 v[220:221], v[96:97], v[148:149], v[156:157]
	v_pk_fma_f32 v[216:217], v[86:87], v[150:151], v[158:159]
	v_pk_fma_f32 v[222:223], v[88:89], v[152:153], v[160:161]
	v_pk_fma_f32 v[214:215], v[138:139], v[110:111], v[214:215]
	v_pk_fma_f32 v[220:221], v[140:141], v[112:113], v[220:221]
	v_pk_fma_f32 v[216:217], v[142:143], v[102:103], v[216:217]
	v_pk_fma_f32 v[222:223], v[144:145], v[104:105], v[222:223]
	v_pk_fma_f32 v[214:215], v[130:131], v[170:171], v[214:215]
	v_pk_fma_f32 v[220:221], v[132:133], v[172:173], v[220:221]
	v_pk_fma_f32 v[216:217], v[134:135], v[174:175], v[216:217]
	v_pk_fma_f32 v[222:223], v[136:137], v[176:177], v[222:223]
	v_pk_mul_f32 v[218:219], v[214:215], s[88:89] op_sel_hi:[1,0]
	v_pk_mul_f32 v[224:225], v[220:221], s[88:89] op_sel_hi:[1,0]
	v_exp_f32_e32 v218, v218
	v_exp_f32_e32 v224, v224
	v_exp_f32_e32 v219, v219
	v_exp_f32_e32 v225, v225
	v_pk_add_f32 v[218:219], v[218:219], 1.0 op_sel_hi:[1,0]
	v_pk_add_f32 v[224:225], v[224:225], 1.0 op_sel_hi:[1,0]
	v_rcp_f32_e32 v218, v218
	v_rcp_f32_e32 v224, v224
	v_rcp_f32_e32 v219, v219
	v_rcp_f32_e32 v225, v225
	v_pk_mul_f32 v[214:215], v[214:215], v[218:219]
	v_pk_mul_f32 v[220:221], v[220:221], v[224:225]
	v_pk_mul_f32 v[214:215], v[216:217], v[214:215]
	v_pk_mul_f32 v[220:221], v[222:223], v[220:221]
	v_cvt_pk_bf16_f32 v230, v214, v215
	v_cvt_pk_bf16_f32 v231, v220, v221
	v_pk_fma_f32 v[214:215], v[114:115], v[146:147], v[154:155]
	v_pk_fma_f32 v[220:221], v[116:117], v[148:149], v[156:157]
	v_pk_fma_f32 v[216:217], v[118:119], v[150:151], v[158:159]
	v_pk_fma_f32 v[222:223], v[120:121], v[152:153], v[160:161]
	v_pk_fma_f32 v[214:215], v[138:139], v[94:95], v[214:215]
	v_pk_fma_f32 v[220:221], v[140:141], v[96:97], v[220:221]
	v_pk_fma_f32 v[216:217], v[142:143], v[86:87], v[216:217]
	v_pk_fma_f32 v[222:223], v[144:145], v[88:89], v[222:223]
	v_pk_fma_f32 v[214:215], v[130:131], v[110:111], v[214:215]
	v_pk_fma_f32 v[220:221], v[132:133], v[112:113], v[220:221]
	v_pk_fma_f32 v[216:217], v[134:135], v[102:103], v[216:217]
	v_pk_fma_f32 v[222:223], v[136:137], v[104:105], v[222:223]
	v_pk_mul_f32 v[218:219], v[214:215], s[88:89] op_sel_hi:[1,0]
	v_pk_mul_f32 v[224:225], v[220:221], s[88:89] op_sel_hi:[1,0]
	v_exp_f32_e32 v218, v218
	v_exp_f32_e32 v224, v224
	v_exp_f32_e32 v219, v219
	v_exp_f32_e32 v225, v225
	v_pk_add_f32 v[218:219], v[218:219], 1.0 op_sel_hi:[1,0]
	v_pk_add_f32 v[224:225], v[224:225], 1.0 op_sel_hi:[1,0]
	v_rcp_f32_e32 v218, v218
	v_rcp_f32_e32 v224, v224
	v_rcp_f32_e32 v219, v219
	v_rcp_f32_e32 v225, v225
	v_pk_mul_f32 v[214:215], v[214:215], v[218:219]
	v_pk_mul_f32 v[220:221], v[220:221], v[224:225]
	v_pk_mul_f32 v[214:215], v[216:217], v[214:215]
	v_pk_mul_f32 v[220:221], v[222:223], v[220:221]
	v_cvt_pk_bf16_f32 v234, v214, v215
	v_cvt_pk_bf16_f32 v235, v220, v221
	v_pk_fma_f32 v[214:215], v[126:127], v[146:147], v[154:155]
	v_pk_fma_f32 v[220:221], v[128:129], v[148:149], v[156:157]
	v_pk_fma_f32 v[216:217], v[122:123], v[150:151], v[158:159]
	v_pk_fma_f32 v[222:223], v[124:125], v[152:153], v[160:161]
	v_pk_fma_f32 v[214:215], v[138:139], v[114:115], v[214:215]
	v_pk_fma_f32 v[220:221], v[140:141], v[116:117], v[220:221]
	v_pk_fma_f32 v[216:217], v[142:143], v[118:119], v[216:217]
	v_pk_fma_f32 v[222:223], v[144:145], v[120:121], v[222:223]
	v_pk_fma_f32 v[214:215], v[130:131], v[94:95], v[214:215]
	v_pk_fma_f32 v[220:221], v[132:133], v[96:97], v[220:221]
	v_pk_fma_f32 v[216:217], v[134:135], v[86:87], v[216:217]
	v_pk_fma_f32 v[222:223], v[136:137], v[88:89], v[222:223]
	v_pk_mul_f32 v[218:219], v[214:215], s[88:89] op_sel_hi:[1,0]
	v_pk_mul_f32 v[224:225], v[220:221], s[88:89] op_sel_hi:[1,0]
	v_exp_f32_e32 v218, v218
	v_exp_f32_e32 v224, v224
	v_exp_f32_e32 v219, v219
	v_exp_f32_e32 v225, v225
	v_pk_add_f32 v[218:219], v[218:219], 1.0 op_sel_hi:[1,0]
	v_pk_add_f32 v[224:225], v[224:225], 1.0 op_sel_hi:[1,0]
	v_rcp_f32_e32 v218, v218
	v_rcp_f32_e32 v224, v224
	v_rcp_f32_e32 v219, v219
	v_rcp_f32_e32 v225, v225
	v_pk_mul_f32 v[214:215], v[214:215], v[218:219]
	v_pk_mul_f32 v[220:221], v[220:221], v[224:225]
	v_pk_mul_f32 v[214:215], v[216:217], v[214:215]
	v_pk_mul_f32 v[220:221], v[222:223], v[220:221]
	v_cvt_pk_bf16_f32 v110, v214, v215
	v_cvt_pk_bf16_f32 v111, v220, v221
	s_and_b64 vcc, exec, s[36:37]
	s_cbranch_vccz .Lffn_hz_2
; #define LAS __attribute__((address_space(3)))
;     __device__ __forceinline__ void operator()(f32x4 (&acc)[2][2][4][2], const Unit& u, int wr, int wc, int fr, int fq, int next_pn) const {
;     ...
;                 if (sl > 0) { const LAS float* hp = H + ((sl - 1) * 2) * 256 + tcol + 4 * hf; hg62 = *(const LAS f32x4*)hp; hv62 = *(const LAS f32x4*)(hp + 128); hg63 = *(const LAS f32x4*)(hp + 256); hv63 = *(const LAS f32x4*)(hp + 384); }
	ds_read_b128 v[162:165], v199 offset:0
	ds_read_b128 v[166:169], v199 offset:512
	ds_read_b128 v[170:173], v199 offset:1024
	ds_read_b128 v[174:177], v199 offset:1536
	s_branch .Lffn_hj_2

;     __device__ __forceinline__ void operator()(f32x4 (&acc)[2][2][4][2], const Unit& u, int wr, int wc, int fr, int fq, int next_pn) const {
;     ...
;                 for (int j = 0; j < 4; ++j) { sg3[j] = dpp_shr1(hg63[j], acc[ai][0][3][hf][j]); sg2[j] = dpp_shr1(hg62[j], acc[ai][0][2][hf][j]); sv3[j] = dpp_shr1(hv63[j], acc[ai][1][3][hf][j]); sv2[j] = dpp_shr1(hv62[j], acc[ai][1][2][hf][j]); }
; #pragma unroll
;                 for (int m = 0; m < 4; ++m) {
;                     const f32x4 cg = acc[ai][0][m][hf], cv = acc[ai][1][m][hf];
;                     const f32x4 g1v = (m == 0) ? sg3 : acc[ai][0][m == 0 ? 0 : m - 1][hf], g2v = (m == 0) ? sg2 : (m == 1) ? sg3 : acc[ai][0][m < 2 ? 0 : m - 2][hf];
;                     const f32x4 v1v = (m == 0) ? sv3 : acc[ai][1][m == 0 ? 0 : m - 1][hf], v2v = (m == 0) ? sv2 : (m == 1) ? sv3 : acc[ai][1][m < 2 ? 0 : m - 2][hf];
;                     float o[4];
; #pragma unroll
;                     for (int j2 = 0; j2 < 2; ++j2) {
;                         const int j = 2 * j2;
;                         const f32x2v g1 = {g1v[j], g1v[j + 1]}, g2 = {g2v[j], g2v[j + 1]}, v1 = {v1v[j], v1v[j + 1]}, v2 = {v2v[j], v2v[j + 1]};
;                         const f32x2v c_g = {cg[j], cg[j + 1]}, c_v = {cv[j], cv[j + 1]};
;                         const f32x2v gc = (f32x2v){wg0[j], wg0[j + 1]} * g2 + ((f32x2v){wg1[j], wg1[j + 1]} * g1 + ((f32x2v){wg2[j], wg2[j + 1]} * c_g + (f32x2v){bg[j], bg[j + 1]}));
;                         const f32x2v vc = (f32x2v){wv0[j], wv0[j + 1]} * v2 + ((f32x2v){wv1[j], wv1[j + 1]} * v1 + ((f32x2v){wv2[j], wv2[j + 1]} * c_v + (f32x2v){bvv[j], bvv[j + 1]}));
;                         const f32x2v e = gc * (-1.4426950408889634f); f32x2v t; t.x = __builtin_amdgcn_exp2f(e.x); t.y = __builtin_amdgcn_exp2f(e.y);
;                         const f32x2v d = t + 1.0f; f32x2v r; r.x = __builtin_amdgcn_rcpf(d.x); r.y = __builtin_amdgcn_rcpf(d.y);
;                         const f32x2v oo = (gc * r) * vc; o[j] = oo.x; o[j + 1] = oo.y; }
;                     u32x2 w; w.x = cvt_pk_bf16(o[0], o[1]); w.y = cvt_pk_bf16(o[2], o[3]);
;                     if (hf == 0) keep[m] = w;
;                     else *(u32x4*)(A2 + (size_t)(rowb + ai * HALF + m) * FFW + c0) = (u32x4){keep[m].x, keep[m].y, w.x, w.y}; }
.Lffn_hj_2:
	s_waitcnt lgkmcnt(0)
	v_mov_b32_dpp v170, v74 row_shr:1 row_mask:0xf bank_mask:0xf
	v_mov_b32_dpp v162, v50 row_shr:1 row_mask:0xf bank_mask:0xf
	v_mov_b32_dpp v174, v78 row_shr:1 row_mask:0xf bank_mask:0xf
	v_mov_b32_dpp v166, v54 row_shr:1 row_mask:0xf bank_mask:0xf
	v_mov_b32_dpp v171, v75 row_shr:1 row_mask:0xf bank_mask:0xf
	v_mov_b32_dpp v163, v51 row_shr:1 row_mask:0xf bank_mask:0xf
	v_mov_b32_dpp v175, v79 row_shr:1 row_mask:0xf bank_mask:0xf
	v_mov_b32_dpp v167, v55 row_shr:1 row_mask:0xf bank_mask:0xf
	v_mov_b32_dpp v172, v76 row_shr:1 row_mask:0xf bank_mask:0xf
	v_mov_b32_dpp v164, v52 row_shr:1 row_mask:0xf bank_mask:0xf
	v_mov_b32_dpp v176, v80 row_shr:1 row_mask:0xf bank_mask:0xf
	v_mov_b32_dpp v168, v56 row_shr:1 row_mask:0xf bank_mask:0xf
	v_mov_b32_dpp v173, v77 row_shr:1 row_mask:0xf bank_mask:0xf
	v_mov_b32_dpp v165, v53 row_shr:1 row_mask:0xf bank_mask:0xf
	v_mov_b32_dpp v177, v81 row_shr:1 row_mask:0xf bank_mask:0xf
	v_mov_b32_dpp v169, v57 row_shr:1 row_mask:0xf bank_mask:0xf
	v_pk_fma_f32 v[214:215], v[46:47], v[146:147], v[154:155]
	v_pk_fma_f32 v[220:221], v[48:49], v[148:149], v[156:157]
	v_pk_fma_f32 v[216:217], v[42:43], v[150:151], v[158:159]
	v_pk_fma_f32 v[222:223], v[44:45], v[152:153], v[160:161]
	v_pk_fma_f32 v[214:215], v[138:139], v[170:171], v[214:215]
	v_pk_fma_f32 v[220:221], v[140:141], v[172:173], v[220:221]
	v_pk_fma_f32 v[216:217], v[142:143], v[174:175], v[216:217]
	v_pk_fma_f32 v[222:223], v[144:145], v[176:177], v[222:223]
	v_pk_fma_f32 v[214:215], v[130:131], v[162:163], v[214:215]
	v_pk_fma_f32 v[220:221], v[132:133], v[164:165], v[220:221]
	v_pk_fma_f32 v[216:217], v[134:135], v[166:167], v[216:217]
	v_pk_fma_f32 v[222:223], v[136:137], v[168:169], v[222:223]
	v_pk_mul_f32 v[218:219], v[214:215], s[88:89] op_sel_hi:[1,0]
	v_pk_mul_f32 v[224:225], v[220:221], s[88:89] op_sel_hi:[1,0]
	v_exp_f32_e32 v218, v218
	v_exp_f32_e32 v224, v224
	v_exp_f32_e32 v219, v219
	v_exp_f32_e32 v225, v225
	v_pk_add_f32 v[218:219], v[218:219], 1.0 op_sel_hi:[1,0]
	v_pk_add_f32 v[224:225], v[224:225], 1.0 op_sel_hi:[1,0]
	v_rcp_f32_e32 v218, v218
	v_rcp_f32_e32 v224, v224
	v_rcp_f32_e32 v219, v219
	v_rcp_f32_e32 v225, v225
	v_pk_mul_f32 v[214:215], v[214:215], v[218:219]
	v_pk_mul_f32 v[220:221], v[220:221], v[224:225]
	v_pk_mul_f32 v[214:215], v[216:217], v[214:215]
	v_pk_mul_f32 v[220:221], v[222:223], v[220:221]
	v_cvt_pk_bf16_f32 v94, v214, v215
	v_cvt_pk_bf16_f32 v95, v220, v221
	v_pk_fma_f32 v[214:215], v[38:39], v[146:147], v[154:155]
	v_pk_fma_f32 v[220:221], v[40:41], v[148:149], v[156:157]
	v_pk_fma_f32 v[216:217], v[26:27], v[150:151], v[158:159]
	v_pk_fma_f32 v[222:223], v[28:29], v[152:153], v[160:161]
	v_pk_fma_f32 v[214:215], v[138:139], v[46:47], v[214:215]
	v_pk_fma_f32 v[220:221], v[140:141], v[48:49], v[220:221]
	v_pk_fma_f32 v[216:217], v[142:143], v[42:43], v[216:217]
	v_pk_fma_f32 v[222:223], v[144:145], v[44:45], v[222:223]
	v_pk_fma_f32 v[214:215], v[130:131], v[170:171], v[214:215]
	v_pk_fma_f32 v[220:221], v[132:133], v[172:173], v[220:221]
	v_pk_fma_f32 v[216:217], v[134:135], v[174:175], v[216:217]
	v_pk_fma_f32 v[222:223], v[136:137], v[176:177], v[222:223]
	v_pk_mul_f32 v[218:219], v[214:215], s[88:89] op_sel_hi:[1,0]
	v_pk_mul_f32 v[224:225], v[220:221], s[88:89] op_sel_hi:[1,0]
	v_exp_f32_e32 v218, v218
	v_exp_f32_e32 v224, v224
	v_exp_f32_e32 v219, v219
	v_exp_f32_e32 v225, v225
	v_pk_add_f32 v[218:219], v[218:219], 1.0 op_sel_hi:[1,0]
	v_pk_add_f32 v[224:225], v[224:225], 1.0 op_sel_hi:[1,0]
	v_rcp_f32_e32 v218, v218
	v_rcp_f32_e32 v224, v224
	v_rcp_f32_e32 v219, v219
	v_rcp_f32_e32 v225, v225
	v_pk_mul_f32 v[214:215], v[214:215], v[218:219]
; #define LAS __attribute__((address_space(3)))
;     __device__ __forceinline__ void operator()(f32x4 (&acc)[2][2][4][2], const Unit& u, int wr, int wc, int fr, int fq, int next_pn) const {
;     ...
;                 const LAS float* wl = WL + tcol + 4 * hf;
;                 const f32x4 wg0 = *(const LAS f32x4*)(wl), wg1 = *(const LAS f32x4*)(wl + 256), wg2 = *(const LAS f32x4*)(wl + 512), bg = *(const LAS f32x4*)(wl + 768);
;                 const f32x4 wv0 = *(const LAS f32x4*)(wl + 128), wv1 = *(const LAS f32x4*)(wl + 384), wv2 = *(const LAS f32x4*)(wl + 640), bvv = *(const LAS f32x4*)(wl + 896);
;                 f32x4 hg62 = (f32x4){0.f, 0.f, 0.f, 0.f}, hg63 = hg62, hv62 = hg62, hv63 = hg62;
;                 if (sl > 0) { const LAS float* hp = H + ((sl - 1) * 2) * 256 + tcol + 4 * hf; hg62 = *(const LAS f32x4*)hp; hv62 = *(const LAS f32x4*)(hp + 128); hg63 = *(const LAS f32x4*)(hp + 256); hv63 = *(const LAS f32x4*)(hp + 384); }
;                 f32x4 sg3, sg2, sv3, sv2;
; #pragma unroll
;                 for (int j = 0; j < 4; ++j) { sg3[j] = dpp_shr1(hg63[j], acc[ai][0][3][hf][j]); sg2[j] = dpp_shr1(hg62[j], acc[ai][0][2][hf][j]); sv3[j] = dpp_shr1(hv63[j], acc[ai][1][3][hf][j]); sv2[j] = dpp_shr1(hv62[j], acc[ai][1][2][hf][j]); }
; #pragma unroll
;                 for (int m = 0; m < 4; ++m) {
;                     const f32x4 cg = acc[ai][0][m][hf], cv = acc[ai][1][m][hf];
;                     const f32x4 g1v = (m == 0) ? sg3 : acc[ai][0][m == 0 ? 0 : m - 1][hf], g2v = (m == 0) ? sg2 : (m == 1) ? sg3 : acc[ai][0][m < 2 ? 0 : m - 2][hf];
;                     const f32x4 v1v = (m == 0) ? sv3 : acc[ai][1][m == 0 ? 0 : m - 1][hf], v2v = (m == 0) ? sv2 : (m == 1) ? sv3 : acc[ai][1][m < 2 ? 0 : m - 2][hf];
;                     float o[4];
; #pragma unroll
;                     for (int j2 = 0; j2 < 2; ++j2) {
;                         const int j = 2 * j2;
;                         const f32x2v g1 = {g1v[j], g1v[j + 1]}, g2 = {g2v[j], g2v[j + 1]}, v1 = {v1v[j], v1v[j + 1]}, v2 = {v2v[j], v2v[j + 1]};
;                         const f32x2v c_g = {cg[j], cg[j + 1]}, c_v = {cv[j], cv[j + 1]};
;                         const f32x2v gc = (f32x2v){wg0[j], wg0[j + 1]} * g2 + ((f32x2v){wg1[j], wg1[j + 1]} * g1 + ((f32x2v){wg2[j], wg2[j + 1]} * c_g + (f32x2v){bg[j], bg[j + 1]}));
	v_pk_mul_f32 v[220:221], v[220:221], v[224:225]
	v_pk_mul_f32 v[214:215], v[216:217], v[214:215]
	v_pk_mul_f32 v[220:221], v[222:223], v[220:221]
	v_cvt_pk_bf16_f32 v114, v214, v215
	v_cvt_pk_bf16_f32 v115, v220, v221
	v_pk_fma_f32 v[214:215], v[50:51], v[146:147], v[154:155]
	v_pk_fma_f32 v[220:221], v[52:53], v[148:149], v[156:157]
	v_pk_fma_f32 v[216:217], v[54:55], v[150:151], v[158:159]
	v_pk_fma_f32 v[222:223], v[56:57], v[152:153], v[160:161]
	v_pk_fma_f32 v[214:215], v[138:139], v[38:39], v[214:215]
	v_pk_fma_f32 v[220:221], v[140:141], v[40:41], v[220:221]
	v_pk_fma_f32 v[216:217], v[142:143], v[26:27], v[216:217]
	v_pk_fma_f32 v[222:223], v[144:145], v[28:29], v[222:223]
	v_pk_fma_f32 v[214:215], v[130:131], v[46:47], v[214:215]
	v_pk_fma_f32 v[220:221], v[132:133], v[48:49], v[220:221]
	v_pk_fma_f32 v[216:217], v[134:135], v[42:43], v[216:217]
	v_pk_fma_f32 v[222:223], v[136:137], v[44:45], v[222:223]
	v_pk_mul_f32 v[218:219], v[214:215], s[88:89] op_sel_hi:[1,0]
	v_pk_mul_f32 v[224:225], v[220:221], s[88:89] op_sel_hi:[1,0]
	v_exp_f32_e32 v218, v218
	v_exp_f32_e32 v224, v224
	v_exp_f32_e32 v219, v219
	v_exp_f32_e32 v225, v225
	v_pk_add_f32 v[218:219], v[218:219], 1.0 op_sel_hi:[1,0]
	v_pk_add_f32 v[224:225], v[224:225], 1.0 op_sel_hi:[1,0]
	v_rcp_f32_e32 v218, v218
	v_rcp_f32_e32 v224, v224
	v_rcp_f32_e32 v219, v219
	v_rcp_f32_e32 v225, v225
	v_pk_mul_f32 v[214:215], v[214:215], v[218:219]
	v_pk_mul_f32 v[220:221], v[220:221], v[224:225]
	v_pk_mul_f32 v[214:215], v[216:217], v[214:215]
	v_pk_mul_f32 v[220:221], v[222:223], v[220:221]
	v_cvt_pk_bf16_f32 v126, v214, v215
	v_cvt_pk_bf16_f32 v127, v220, v221
	v_pk_fma_f32 v[214:215], v[74:75], v[146:147], v[154:155]
	v_pk_fma_f32 v[220:221], v[76:77], v[148:149], v[156:157]
	v_pk_fma_f32 v[216:217], v[78:79], v[150:151], v[158:159]
	v_pk_fma_f32 v[222:223], v[80:81], v[152:153], v[160:161]
	v_pk_fma_f32 v[214:215], v[138:139], v[50:51], v[214:215]
	v_pk_fma_f32 v[220:221], v[140:141], v[52:53], v[220:221]
	v_pk_fma_f32 v[216:217], v[142:143], v[54:55], v[216:217]
	v_pk_fma_f32 v[222:223], v[144:145], v[56:57], v[222:223]
	v_pk_fma_f32 v[214:215], v[130:131], v[38:39], v[214:215]
	v_pk_fma_f32 v[220:221], v[132:133], v[40:41], v[220:221]
	v_pk_fma_f32 v[216:217], v[134:135], v[26:27], v[216:217]
	v_pk_fma_f32 v[222:223], v[136:137], v[28:29], v[222:223]
	v_pk_mul_f32 v[218:219], v[214:215], s[88:89] op_sel_hi:[1,0]
	v_pk_mul_f32 v[224:225], v[220:221], s[88:89] op_sel_hi:[1,0]
	v_exp_f32_e32 v218, v218
	v_exp_f32_e32 v224, v224
	v_exp_f32_e32 v219, v219
	v_exp_f32_e32 v225, v225
	v_pk_add_f32 v[218:219], v[218:219], 1.0 op_sel_hi:[1,0]
	v_pk_add_f32 v[224:225], v[224:225], 1.0 op_sel_hi:[1,0]
	v_rcp_f32_e32 v218, v218
	v_rcp_f32_e32 v224, v224
	v_rcp_f32_e32 v219, v219
	v_rcp_f32_e32 v225, v225
	v_pk_mul_f32 v[214:215], v[214:215], v[218:219]
	v_pk_mul_f32 v[220:221], v[220:221], v[224:225]
	v_pk_mul_f32 v[214:215], v[216:217], v[214:215]
	v_pk_mul_f32 v[220:221], v[222:223], v[220:221]
	v_cvt_pk_bf16_f32 v102, v214, v215
	v_cvt_pk_bf16_f32 v103, v220, v221
	ds_read_b128 v[130:133], v197 offset:16
	ds_read_b128 v[134:137], v197 offset:528
	ds_read_b128 v[138:141], v197 offset:1040
	ds_read_b128 v[142:145], v197 offset:1552
	ds_read_b128 v[146:149], v197 offset:2064
	ds_read_b128 v[150:153], v197 offset:2576
	ds_read_b128 v[154:157], v197 offset:3088
	ds_read_b128 v[158:161], v197 offset:3600
	s_and_b64 vcc, exec, s[34:35]
	s_cbranch_vccz .Lffn_hz_3
	ds_read_b128 v[162:165], v198 offset:16
	ds_read_b128 v[166:169], v198 offset:528
	ds_read_b128 v[170:173], v198 offset:1040
	ds_read_b128 v[174:177], v198 offset:1552
	s_branch .Lffn_hj_3

;     __device__ __forceinline__ void operator()(f32x4 (&acc)[2][2][4][2], const Unit& u, int wr, int wc, int fr, int fq, int next_pn) const {
;     ...
;                 for (int j = 0; j < 4; ++j) { sg3[j] = dpp_shr1(hg63[j], acc[ai][0][3][hf][j]); sg2[j] = dpp_shr1(hg62[j], acc[ai][0][2][hf][j]); sv3[j] = dpp_shr1(hv63[j], acc[ai][1][3][hf][j]); sv2[j] = dpp_shr1(hv62[j], acc[ai][1][2][hf][j]); }
; #pragma unroll
;                 for (int m = 0; m < 4; ++m) {
;                     const f32x4 cg = acc[ai][0][m][hf], cv = acc[ai][1][m][hf];
;                     const f32x4 g1v = (m == 0) ? sg3 : acc[ai][0][m == 0 ? 0 : m - 1][hf], g2v = (m == 0) ? sg2 : (m == 1) ? sg3 : acc[ai][0][m < 2 ? 0 : m - 2][hf];
;                     const f32x4 v1v = (m == 0) ? sv3 : acc[ai][1][m == 0 ? 0 : m - 1][hf], v2v = (m == 0) ? sv2 : (m == 1) ? sv3 : acc[ai][1][m < 2 ? 0 : m - 2][hf];
;                     float o[4];
; #pragma unroll
;                     for (int j2 = 0; j2 < 2; ++j2) {
;                         const int j = 2 * j2;
;                         const f32x2v g1 = {g1v[j], g1v[j + 1]}, g2 = {g2v[j], g2v[j + 1]}, v1 = {v1v[j], v1v[j + 1]}, v2 = {v2v[j], v2v[j + 1]};
;                         const f32x2v c_g = {cg[j], cg[j + 1]}, c_v = {cv[j], cv[j + 1]};
;                         const f32x2v gc = (f32x2v){wg0[j], wg0[j + 1]} * g2 + ((f32x2v){wg1[j], wg1[j + 1]} * g1 + ((f32x2v){wg2[j], wg2[j + 1]} * c_g + (f32x2v){bg[j], bg[j + 1]}));
;                         const f32x2v vc = (f32x2v){wv0[j], wv0[j + 1]} * v2 + ((f32x2v){wv1[j], wv1[j + 1]} * v1 + ((f32x2v){wv2[j], wv2[j + 1]} * c_v + (f32x2v){bvv[j], bvv[j + 1]}));
;                         const f32x2v e = gc * (-1.4426950408889634f); f32x2v t; t.x = __builtin_amdgcn_exp2f(e.x); t.y = __builtin_amdgcn_exp2f(e.y);
;                         const f32x2v d = t + 1.0f; f32x2v r; r.x = __builtin_amdgcn_rcpf(d.x); r.y = __builtin_amdgcn_rcpf(d.y);
;                         const f32x2v oo = (gc * r) * vc; o[j] = oo.x; o[j + 1] = oo.y; }
;                     u32x2 w; w.x = cvt_pk_bf16(o[0], o[1]); w.y = cvt_pk_bf16(o[2], o[3]);
;                     if (hf == 0) keep[m] = w;
;                     else *(u32x4*)(A2 + (size_t)(rowb + ai * HALF + m) * FFW + c0) = (u32x4){keep[m].x, keep[m].y, w.x, w.y}; }
.Lffn_hj_3:
	s_waitcnt lgkmcnt(0)
	v_mov_b32_dpp v170, v70 row_shr:1 row_mask:0xf bank_mask:0xf
	v_mov_b32_dpp v162, v62 row_shr:1 row_mask:0xf bank_mask:0xf
	v_mov_b32_dpp v174, v66 row_shr:1 row_mask:0xf bank_mask:0xf
	v_mov_b32_dpp v166, v58 row_shr:1 row_mask:0xf bank_mask:0xf
	v_mov_b32_dpp v171, v71 row_shr:1 row_mask:0xf bank_mask:0xf
	v_mov_b32_dpp v163, v63 row_shr:1 row_mask:0xf bank_mask:0xf
	v_mov_b32_dpp v175, v67 row_shr:1 row_mask:0xf bank_mask:0xf
	v_mov_b32_dpp v167, v59 row_shr:1 row_mask:0xf bank_mask:0xf
	v_mov_b32_dpp v172, v72 row_shr:1 row_mask:0xf bank_mask:0xf
	v_mov_b32_dpp v164, v64 row_shr:1 row_mask:0xf bank_mask:0xf
	v_mov_b32_dpp v176, v68 row_shr:1 row_mask:0xf bank_mask:0xf
	v_mov_b32_dpp v168, v60 row_shr:1 row_mask:0xf bank_mask:0xf
	v_mov_b32_dpp v173, v73 row_shr:1 row_mask:0xf bank_mask:0xf
	v_mov_b32_dpp v165, v65 row_shr:1 row_mask:0xf bank_mask:0xf
	v_mov_b32_dpp v177, v69 row_shr:1 row_mask:0xf bank_mask:0xf
	v_mov_b32_dpp v169, v61 row_shr:1 row_mask:0xf bank_mask:0xf
	v_pk_fma_f32 v[214:215], v[106:107], v[146:147], v[154:155]
	v_pk_fma_f32 v[220:221], v[108:109], v[148:149], v[156:157]
	v_pk_fma_f32 v[216:217], v[98:99], v[150:151], v[158:159]
	v_pk_fma_f32 v[222:223], v[100:101], v[152:153], v[160:161]
	v_pk_fma_f32 v[214:215], v[138:139], v[170:171], v[214:215]
	v_pk_fma_f32 v[220:221], v[140:141], v[172:173], v[220:221]
	v_pk_fma_f32 v[216:217], v[142:143], v[174:175], v[216:217]
	v_pk_fma_f32 v[222:223], v[144:145], v[176:177], v[222:223]
	v_pk_fma_f32 v[214:215], v[130:131], v[162:163], v[214:215]
	v_pk_fma_f32 v[220:221], v[132:133], v[164:165], v[220:221]
	v_pk_fma_f32 v[216:217], v[134:135], v[166:167], v[216:217]
	v_pk_fma_f32 v[222:223], v[136:137], v[168:169], v[222:223]
	v_pk_mul_f32 v[218:219], v[214:215], s[88:89] op_sel_hi:[1,0]
	v_pk_mul_f32 v[224:225], v[220:221], s[88:89] op_sel_hi:[1,0]
	v_exp_f32_e32 v218, v218
	v_exp_f32_e32 v224, v224
	v_exp_f32_e32 v219, v219
	v_exp_f32_e32 v225, v225
	v_pk_add_f32 v[218:219], v[218:219], 1.0 op_sel_hi:[1,0]
	v_pk_add_f32 v[224:225], v[224:225], 1.0 op_sel_hi:[1,0]
	v_rcp_f32_e32 v218, v218
	v_rcp_f32_e32 v224, v224
	v_rcp_f32_e32 v219, v219
	v_rcp_f32_e32 v225, v225
	v_pk_mul_f32 v[214:215], v[214:215], v[218:219]
	v_pk_mul_f32 v[220:221], v[220:221], v[224:225]
	v_pk_mul_f32 v[214:215], v[216:217], v[214:215]
	v_pk_mul_f32 v[220:221], v[222:223], v[220:221]
	v_cvt_pk_bf16_f32 v228, v214, v215
	v_cvt_pk_bf16_f32 v229, v220, v221
	global_store_dwordx4 v[210:211], v[226:229], off
	v_lshl_add_u64 v[210:211], v[210:211], 0, s[98:99]
	v_pk_fma_f32 v[214:215], v[90:91], v[146:147], v[154:155]
	v_pk_fma_f32 v[220:221], v[92:93], v[148:149], v[156:157]
	v_pk_fma_f32 v[216:217], v[82:83], v[150:151], v[158:159]
	v_pk_fma_f32 v[222:223], v[84:85], v[152:153], v[160:161]
	v_pk_fma_f32 v[214:215], v[138:139], v[106:107], v[214:215]
	v_pk_fma_f32 v[220:221], v[140:141], v[108:109], v[220:221]
	v_pk_fma_f32 v[216:217], v[142:143], v[98:99], v[216:217]
	v_pk_fma_f32 v[222:223], v[144:145], v[100:101], v[222:223]
	v_pk_fma_f32 v[214:215], v[130:131], v[170:171], v[214:215]
	v_pk_fma_f32 v[220:221], v[132:133], v[172:173], v[220:221]
	v_pk_fma_f32 v[216:217], v[134:135], v[174:175], v[216:217]
	v_pk_fma_f32 v[222:223], v[136:137], v[176:177], v[222:223]
	v_pk_mul_f32 v[218:219], v[214:215], s[88:89] op_sel_hi:[1,0]
	v_pk_mul_f32 v[224:225], v[220:221], s[88:89] op_sel_hi:[1,0]
	v_exp_f32_e32 v218, v218
	v_exp_f32_e32 v224, v224
	v_exp_f32_e32 v219, v219
	v_exp_f32_e32 v225, v225
	v_pk_add_f32 v[218:219], v[218:219], 1.0 op_sel_hi:[1,0]
	v_pk_add_f32 v[224:225], v[224:225], 1.0 op_sel_hi:[1,0]
	v_rcp_f32_e32 v218, v218
	v_rcp_f32_e32 v224, v224
	v_rcp_f32_e32 v219, v219
	v_rcp_f32_e32 v225, v225
; __device__ __forceinline__ unsigned cvt_pk_bf16(float lo, float hi) { unsigned r; asm("v_cvt_pk_bf16_f32 %0, %1, %2" : "=v"(r) : "v"(lo), "v"(hi)); return r; }
;     __device__ __forceinline__ void operator()(f32x4 (&acc)[2][2][4][2], const Unit& u, int wr, int wc, int fr, int fq, int next_pn) const {
;     ...
;                 for (int m = 0; m < 4; ++m) {
;                     const f32x4 cg = acc[ai][0][m][hf], cv = acc[ai][1][m][hf];
;                     const f32x4 g1v = (m == 0) ? sg3 : acc[ai][0][m == 0 ? 0 : m - 1][hf], g2v = (m == 0) ? sg2 : (m == 1) ? sg3 : acc[ai][0][m < 2 ? 0 : m - 2][hf];
;                     const f32x4 v1v = (m == 0) ? sv3 : acc[ai][1][m == 0 ? 0 : m - 1][hf], v2v = (m == 0) ? sv2 : (m == 1) ? sv3 : acc[ai][1][m < 2 ? 0 : m - 2][hf];
;                     float o[4];
; #pragma unroll
;                     for (int j2 = 0; j2 < 2; ++j2) {
;                         const int j = 2 * j2;
;                         const f32x2v g1 = {g1v[j], g1v[j + 1]}, g2 = {g2v[j], g2v[j + 1]}, v1 = {v1v[j], v1v[j + 1]}, v2 = {v2v[j], v2v[j + 1]};
;                         const f32x2v c_g = {cg[j], cg[j + 1]}, c_v = {cv[j], cv[j + 1]};
;                         const f32x2v gc = (f32x2v){wg0[j], wg0[j + 1]} * g2 + ((f32x2v){wg1[j], wg1[j + 1]} * g1 + ((f32x2v){wg2[j], wg2[j + 1]} * c_g + (f32x2v){bg[j], bg[j + 1]}));
;                         const f32x2v vc = (f32x2v){wv0[j], wv0[j + 1]} * v2 + ((f32x2v){wv1[j], wv1[j + 1]} * v1 + ((f32x2v){wv2[j], wv2[j + 1]} * c_v + (f32x2v){bvv[j], bvv[j + 1]}));
;                         const f32x2v e = gc * (-1.4426950408889634f); f32x2v t; t.x = __builtin_amdgcn_exp2f(e.x); t.y = __builtin_amdgcn_exp2f(e.y);
;                         const f32x2v d = t + 1.0f; f32x2v r; r.x = __builtin_amdgcn_rcpf(d.x); r.y = __builtin_amdgcn_rcpf(d.y);
;                         const f32x2v oo = (gc * r) * vc; o[j] = oo.x; o[j + 1] = oo.y; }
;                     u32x2 w; w.x = cvt_pk_bf16(o[0], o[1]); w.y = cvt_pk_bf16(o[2], o[3]);
;                     if (hf == 0) keep[m] = w;
;                     else *(u32x4*)(A2 + (size_t)(rowb + ai * HALF + m) * FFW + c0) = (u32x4){keep[m].x, keep[m].y, w.x, w.y}; }
	v_pk_mul_f32 v[214:215], v[214:215], v[218:219]
	v_pk_mul_f32 v[220:221], v[220:221], v[224:225]
	v_pk_mul_f32 v[214:215], v[216:217], v[214:215]
	v_pk_mul_f32 v[220:221], v[222:223], v[220:221]
	v_cvt_pk_bf16_f32 v232, v214, v215
	v_cvt_pk_bf16_f32 v233, v220, v221
	global_store_dwordx4 v[210:211], v[230:233], off
	v_lshl_add_u64 v[210:211], v[210:211], 0, s[98:99]
	v_pk_fma_f32 v[214:215], v[62:63], v[146:147], v[154:155]
	v_pk_fma_f32 v[220:221], v[64:65], v[148:149], v[156:157]
	v_pk_fma_f32 v[216:217], v[58:59], v[150:151], v[158:159]
	v_pk_fma_f32 v[222:223], v[60:61], v[152:153], v[160:161]
	v_pk_fma_f32 v[214:215], v[138:139], v[90:91], v[214:215]
	v_pk_fma_f32 v[220:221], v[140:141], v[92:93], v[220:221]
	v_pk_fma_f32 v[216:217], v[142:143], v[82:83], v[216:217]
	v_pk_fma_f32 v[222:223], v[144:145], v[84:85], v[222:223]
	v_pk_fma_f32 v[214:215], v[130:131], v[106:107], v[214:215]
	v_pk_fma_f32 v[220:221], v[132:133], v[108:109], v[220:221]
	v_pk_fma_f32 v[216:217], v[134:135], v[98:99], v[216:217]
	v_pk_fma_f32 v[222:223], v[136:137], v[100:101], v[222:223]
	v_pk_mul_f32 v[218:219], v[214:215], s[88:89] op_sel_hi:[1,0]
	v_pk_mul_f32 v[224:225], v[220:221], s[88:89] op_sel_hi:[1,0]
	v_exp_f32_e32 v218, v218
	v_exp_f32_e32 v224, v224
	v_exp_f32_e32 v219, v219
	v_exp_f32_e32 v225, v225
	v_pk_add_f32 v[218:219], v[218:219], 1.0 op_sel_hi:[1,0]
	v_pk_add_f32 v[224:225], v[224:225], 1.0 op_sel_hi:[1,0]
	v_rcp_f32_e32 v218, v218
	v_rcp_f32_e32 v224, v224
	v_rcp_f32_e32 v219, v219
	v_rcp_f32_e32 v225, v225
	v_pk_mul_f32 v[214:215], v[214:215], v[218:219]
	v_pk_mul_f32 v[220:221], v[220:221], v[224:225]
	v_pk_mul_f32 v[214:215], v[216:217], v[214:215]
	v_pk_mul_f32 v[220:221], v[222:223], v[220:221]
	v_cvt_pk_bf16_f32 v236, v214, v215
	v_cvt_pk_bf16_f32 v237, v220, v221
	global_store_dwordx4 v[210:211], v[234:237], off
	v_lshl_add_u64 v[210:211], v[210:211], 0, s[98:99]
	v_pk_fma_f32 v[214:215], v[70:71], v[146:147], v[154:155]
	v_pk_fma_f32 v[220:221], v[72:73], v[148:149], v[156:157]
	v_pk_fma_f32 v[216:217], v[66:67], v[150:151], v[158:159]
	v_pk_fma_f32 v[222:223], v[68:69], v[152:153], v[160:161]
	v_pk_fma_f32 v[214:215], v[138:139], v[62:63], v[214:215]
	v_pk_fma_f32 v[220:221], v[140:141], v[64:65], v[220:221]
	v_pk_fma_f32 v[216:217], v[142:143], v[58:59], v[216:217]
	v_pk_fma_f32 v[222:223], v[144:145], v[60:61], v[222:223]
	v_pk_fma_f32 v[214:215], v[130:131], v[90:91], v[214:215]
	v_pk_fma_f32 v[220:221], v[132:133], v[92:93], v[220:221]
	v_pk_fma_f32 v[216:217], v[134:135], v[82:83], v[216:217]
	v_pk_fma_f32 v[222:223], v[136:137], v[84:85], v[222:223]
	v_pk_mul_f32 v[218:219], v[214:215], s[88:89] op_sel_hi:[1,0]
	v_pk_mul_f32 v[224:225], v[220:221], s[88:89] op_sel_hi:[1,0]
	v_exp_f32_e32 v218, v218
	v_exp_f32_e32 v224, v224
	v_exp_f32_e32 v219, v219
	v_exp_f32_e32 v225, v225
	v_pk_add_f32 v[218:219], v[218:219], 1.0 op_sel_hi:[1,0]
	v_pk_add_f32 v[224:225], v[224:225], 1.0 op_sel_hi:[1,0]
	v_rcp_f32_e32 v218, v218
	v_rcp_f32_e32 v224, v224
	v_rcp_f32_e32 v219, v219
	v_rcp_f32_e32 v225, v225
	v_pk_mul_f32 v[214:215], v[214:215], v[218:219]
	v_pk_mul_f32 v[220:221], v[220:221], v[224:225]
	v_pk_mul_f32 v[214:215], v[216:217], v[214:215]
	v_pk_mul_f32 v[220:221], v[222:223], v[220:221]
	v_cvt_pk_bf16_f32 v112, v214, v215
	v_cvt_pk_bf16_f32 v113, v220, v221
	global_store_dwordx4 v[210:211], v[110:113], off
	s_mov_b32 s98, 0xaa800
	v_lshl_add_u64 v[210:211], v[210:211], 0, s[98:99]
	s_mov_b32 s98, 0x1600
	v_lshl_add_u64 v[210:211], v[210:211], 0, s[98:99]
	s_and_b64 vcc, exec, s[36:37]
	s_cbranch_vccz .Lffn_hz_4
	ds_read_b128 v[162:165], v199 offset:16
	ds_read_b128 v[166:169], v199 offset:528
	ds_read_b128 v[170:173], v199 offset:1040
	ds_read_b128 v[174:177], v199 offset:1552
	s_branch .Lffn_hj_4

;     __device__ __forceinline__ void operator()(f32x4 (&acc)[2][2][4][2], const Unit& u, int wr, int wc, int fr, int fq, int next_pn) const {
;     ...
;                 for (int j = 0; j < 4; ++j) { sg3[j] = dpp_shr1(hg63[j], acc[ai][0][3][hf][j]); sg2[j] = dpp_shr1(hg62[j], acc[ai][0][2][hf][j]); sv3[j] = dpp_shr1(hv63[j], acc[ai][1][3][hf][j]); sv2[j] = dpp_shr1(hv62[j], acc[ai][1][2][hf][j]); }
; #pragma unroll
;                 for (int m = 0; m < 4; ++m) {
;                     const f32x4 cg = acc[ai][0][m][hf], cv = acc[ai][1][m][hf];
;                     const f32x4 g1v = (m == 0) ? sg3 : acc[ai][0][m == 0 ? 0 : m - 1][hf], g2v = (m == 0) ? sg2 : (m == 1) ? sg3 : acc[ai][0][m < 2 ? 0 : m - 2][hf];
;                     const f32x4 v1v = (m == 0) ? sv3 : acc[ai][1][m == 0 ? 0 : m - 1][hf], v2v = (m == 0) ? sv2 : (m == 1) ? sv3 : acc[ai][1][m < 2 ? 0 : m - 2][hf];
;                     float o[4];
; #pragma unroll
;                     for (int j2 = 0; j2 < 2; ++j2) {
;                         const int j = 2 * j2;
;                         const f32x2v g1 = {g1v[j], g1v[j + 1]}, g2 = {g2v[j], g2v[j + 1]}, v1 = {v1v[j], v1v[j + 1]}, v2 = {v2v[j], v2v[j + 1]};
;                         const f32x2v c_g = {cg[j], cg[j + 1]}, c_v = {cv[j], cv[j + 1]};
;                         const f32x2v gc = (f32x2v){wg0[j], wg0[j + 1]} * g2 + ((f32x2v){wg1[j], wg1[j + 1]} * g1 + ((f32x2v){wg2[j], wg2[j + 1]} * c_g + (f32x2v){bg[j], bg[j + 1]}));
;                         const f32x2v vc = (f32x2v){wv0[j], wv0[j + 1]} * v2 + ((f32x2v){wv1[j], wv1[j + 1]} * v1 + ((f32x2v){wv2[j], wv2[j + 1]} * c_v + (f32x2v){bvv[j], bvv[j + 1]}));
;                         const f32x2v e = gc * (-1.4426950408889634f); f32x2v t; t.x = __builtin_amdgcn_exp2f(e.x); t.y = __builtin_amdgcn_exp2f(e.y);
;                         const f32x2v d = t + 1.0f; f32x2v r; r.x = __builtin_amdgcn_rcpf(d.x); r.y = __builtin_amdgcn_rcpf(d.y);
;                         const f32x2v oo = (gc * r) * vc; o[j] = oo.x; o[j + 1] = oo.y; }
;                     u32x2 w; w.x = cvt_pk_bf16(o[0], o[1]); w.y = cvt_pk_bf16(o[2], o[3]);
;                     if (hf == 0) keep[m] = w;
;                     else *(u32x4*)(A2 + (size_t)(rowb + ai * HALF + m) * FFW + c0) = (u32x4){keep[m].x, keep[m].y, w.x, w.y}; }
.Lffn_hj_4:
	s_waitcnt lgkmcnt(0)
	v_mov_b32_dpp v170, v10 row_shr:1 row_mask:0xf bank_mask:0xf
	v_mov_b32_dpp v162, v2 row_shr:1 row_mask:0xf bank_mask:0xf
	v_mov_b32_dpp v174, v14 row_shr:1 row_mask:0xf bank_mask:0xf
	v_mov_b32_dpp v166, v6 row_shr:1 row_mask:0xf bank_mask:0xf
	v_mov_b32_dpp v171, v11 row_shr:1 row_mask:0xf bank_mask:0xf
	v_mov_b32_dpp v163, v3 row_shr:1 row_mask:0xf bank_mask:0xf
	v_mov_b32_dpp v175, v15 row_shr:1 row_mask:0xf bank_mask:0xf
	v_mov_b32_dpp v167, v7 row_shr:1 row_mask:0xf bank_mask:0xf
	v_mov_b32_dpp v172, v12 row_shr:1 row_mask:0xf bank_mask:0xf
	v_mov_b32_dpp v164, v4 row_shr:1 row_mask:0xf bank_mask:0xf
	v_mov_b32_dpp v176, v16 row_shr:1 row_mask:0xf bank_mask:0xf
	v_mov_b32_dpp v168, v8 row_shr:1 row_mask:0xf bank_mask:0xf
	v_mov_b32_dpp v173, v13 row_shr:1 row_mask:0xf bank_mask:0xf
	v_mov_b32_dpp v165, v5 row_shr:1 row_mask:0xf bank_mask:0xf
	v_mov_b32_dpp v177, v17 row_shr:1 row_mask:0xf bank_mask:0xf
	v_mov_b32_dpp v169, v9 row_shr:1 row_mask:0xf bank_mask:0xf
	v_pk_fma_f32 v[214:215], v[30:31], v[146:147], v[154:155]
	v_pk_fma_f32 v[220:221], v[32:33], v[148:149], v[156:157]
	v_pk_fma_f32 v[216:217], v[34:35], v[150:151], v[158:159]
	v_pk_fma_f32 v[222:223], v[36:37], v[152:153], v[160:161]
	v_pk_fma_f32 v[214:215], v[138:139], v[170:171], v[214:215]
	v_pk_fma_f32 v[220:221], v[140:141], v[172:173], v[220:221]
	v_pk_fma_f32 v[216:217], v[142:143], v[174:175], v[216:217]
	v_pk_fma_f32 v[222:223], v[144:145], v[176:177], v[222:223]
	v_pk_fma_f32 v[214:215], v[130:131], v[162:163], v[214:215]
	v_pk_fma_f32 v[220:221], v[132:133], v[164:165], v[220:221]
	v_pk_fma_f32 v[216:217], v[134:135], v[166:167], v[216:217]
	v_pk_fma_f32 v[222:223], v[136:137], v[168:169], v[222:223]
	v_pk_mul_f32 v[218:219], v[214:215], s[88:89] op_sel_hi:[1,0]
	v_pk_mul_f32 v[224:225], v[220:221], s[88:89] op_sel_hi:[1,0]
	v_exp_f32_e32 v218, v218
	v_exp_f32_e32 v224, v224
	v_exp_f32_e32 v219, v219
	v_exp_f32_e32 v225, v225
	v_pk_add_f32 v[218:219], v[218:219], 1.0 op_sel_hi:[1,0]
	v_pk_add_f32 v[224:225], v[224:225], 1.0 op_sel_hi:[1,0]
	v_rcp_f32_e32 v218, v218
	v_rcp_f32_e32 v224, v224
	v_rcp_f32_e32 v219, v219
	v_rcp_f32_e32 v225, v225
	v_pk_mul_f32 v[214:215], v[214:215], v[218:219]
	v_pk_mul_f32 v[220:221], v[220:221], v[224:225]
	v_pk_mul_f32 v[214:215], v[216:217], v[214:215]
	v_pk_mul_f32 v[220:221], v[222:223], v[220:221]
	v_cvt_pk_bf16_f32 v96, v214, v215
	v_cvt_pk_bf16_f32 v97, v220, v221
	global_store_dwordx4 v[210:211], v[94:97], off
	v_lshl_add_u64 v[210:211], v[210:211], 0, s[98:99]
	v_pk_fma_f32 v[214:215], v[18:19], v[146:147], v[154:155]
	v_pk_fma_f32 v[220:221], v[20:21], v[148:149], v[156:157]
	v_pk_fma_f32 v[216:217], v[22:23], v[150:151], v[158:159]
	v_pk_fma_f32 v[222:223], v[24:25], v[152:153], v[160:161]
	v_pk_fma_f32 v[214:215], v[138:139], v[30:31], v[214:215]
	v_pk_fma_f32 v[220:221], v[140:141], v[32:33], v[220:221]
	v_pk_fma_f32 v[216:217], v[142:143], v[34:35], v[216:217]
	v_pk_fma_f32 v[222:223], v[144:145], v[36:37], v[222:223]
	v_pk_fma_f32 v[214:215], v[130:131], v[170:171], v[214:215]
	v_pk_fma_f32 v[220:221], v[132:133], v[172:173], v[220:221]
	v_pk_fma_f32 v[216:217], v[134:135], v[174:175], v[216:217]
	v_pk_fma_f32 v[222:223], v[136:137], v[176:177], v[222:223]
	v_pk_mul_f32 v[218:219], v[214:215], s[88:89] op_sel_hi:[1,0]
	v_pk_mul_f32 v[224:225], v[220:221], s[88:89] op_sel_hi:[1,0]
	v_exp_f32_e32 v218, v218
	v_exp_f32_e32 v224, v224
	v_exp_f32_e32 v219, v219
	v_exp_f32_e32 v225, v225
	v_pk_add_f32 v[218:219], v[218:219], 1.0 op_sel_hi:[1,0]
	v_pk_add_f32 v[224:225], v[224:225], 1.0 op_sel_hi:[1,0]
	v_rcp_f32_e32 v218, v218
	v_rcp_f32_e32 v224, v224
; #define LAS __attribute__((address_space(3)))
; __device__ __forceinline__ unsigned cvt_pk_bf16(float lo, float hi) { unsigned r; asm("v_cvt_pk_bf16_f32 %0, %1, %2" : "=v"(r) : "v"(lo), "v"(hi)); return r; }
;     __device__ __forceinline__ void operator()(f32x4 (&acc)[2][2][4][2], const Unit& u, int wr, int wc, int fr, int fq, int next_pn) const {
;     ...
;                 for (int m = 0; m < 4; ++m) {
;                     const f32x4 cg = acc[ai][0][m][hf], cv = acc[ai][1][m][hf];
;                     const f32x4 g1v = (m == 0) ? sg3 : acc[ai][0][m == 0 ? 0 : m - 1][hf], g2v = (m == 0) ? sg2 : (m == 1) ? sg3 : acc[ai][0][m < 2 ? 0 : m - 2][hf];
;                     const f32x4 v1v = (m == 0) ? sv3 : acc[ai][1][m == 0 ? 0 : m - 1][hf], v2v = (m == 0) ? sv2 : (m == 1) ? sv3 : acc[ai][1][m < 2 ? 0 : m - 2][hf];
;                     float o[4];
; #pragma unroll
;                     for (int j2 = 0; j2 < 2; ++j2) {
;                         const int j = 2 * j2;
;                         const f32x2v g1 = {g1v[j], g1v[j + 1]}, g2 = {g2v[j], g2v[j + 1]}, v1 = {v1v[j], v1v[j + 1]}, v2 = {v2v[j], v2v[j + 1]};
;                         const f32x2v c_g = {cg[j], cg[j + 1]}, c_v = {cv[j], cv[j + 1]};
;                         const f32x2v gc = (f32x2v){wg0[j], wg0[j + 1]} * g2 + ((f32x2v){wg1[j], wg1[j + 1]} * g1 + ((f32x2v){wg2[j], wg2[j + 1]} * c_g + (f32x2v){bg[j], bg[j + 1]}));
;                         const f32x2v vc = (f32x2v){wv0[j], wv0[j + 1]} * v2 + ((f32x2v){wv1[j], wv1[j + 1]} * v1 + ((f32x2v){wv2[j], wv2[j + 1]} * c_v + (f32x2v){bvv[j], bvv[j + 1]}));
;                         const f32x2v e = gc * (-1.4426950408889634f); f32x2v t; t.x = __builtin_amdgcn_exp2f(e.x); t.y = __builtin_amdgcn_exp2f(e.y);
;                         const f32x2v d = t + 1.0f; f32x2v r; r.x = __builtin_amdgcn_rcpf(d.x); r.y = __builtin_amdgcn_rcpf(d.y);
;                         const f32x2v oo = (gc * r) * vc; o[j] = oo.x; o[j + 1] = oo.y; }
;                     u32x2 w; w.x = cvt_pk_bf16(o[0], o[1]); w.y = cvt_pk_bf16(o[2], o[3]);
;                     if (hf == 0) keep[m] = w;
;                     else *(u32x4*)(A2 + (size_t)(rowb + ai * HALF + m) * FFW + c0) = (u32x4){keep[m].x, keep[m].y, w.x, w.y}; }
;             }
;             __builtin_amdgcn_sched_barrier(0);
;         }
;         if (next_pn >= 0) { *(LAS f32x2v*)(WL0 + (1 - bcur) * 1024 + wl_idx) = wn2; }
	v_rcp_f32_e32 v219, v219
	v_rcp_f32_e32 v225, v225
	v_pk_mul_f32 v[214:215], v[214:215], v[218:219]
	v_pk_mul_f32 v[220:221], v[220:221], v[224:225]
	v_pk_mul_f32 v[214:215], v[216:217], v[214:215]
	v_pk_mul_f32 v[220:221], v[222:223], v[220:221]
	v_cvt_pk_bf16_f32 v116, v214, v215
	v_cvt_pk_bf16_f32 v117, v220, v221
	global_store_dwordx4 v[210:211], v[114:117], off
	v_lshl_add_u64 v[210:211], v[210:211], 0, s[98:99]
	v_pk_fma_f32 v[214:215], v[2:3], v[146:147], v[154:155]
	v_pk_fma_f32 v[220:221], v[4:5], v[148:149], v[156:157]
	v_pk_fma_f32 v[216:217], v[6:7], v[150:151], v[158:159]
	v_pk_fma_f32 v[222:223], v[8:9], v[152:153], v[160:161]
	v_pk_fma_f32 v[214:215], v[138:139], v[18:19], v[214:215]
	v_pk_fma_f32 v[220:221], v[140:141], v[20:21], v[220:221]
	v_pk_fma_f32 v[216:217], v[142:143], v[22:23], v[216:217]
	v_pk_fma_f32 v[222:223], v[144:145], v[24:25], v[222:223]
	v_pk_fma_f32 v[214:215], v[130:131], v[30:31], v[214:215]
	v_pk_fma_f32 v[220:221], v[132:133], v[32:33], v[220:221]
	v_pk_fma_f32 v[216:217], v[134:135], v[34:35], v[216:217]
	v_pk_fma_f32 v[222:223], v[136:137], v[36:37], v[222:223]
	v_pk_mul_f32 v[218:219], v[214:215], s[88:89] op_sel_hi:[1,0]
	v_pk_mul_f32 v[224:225], v[220:221], s[88:89] op_sel_hi:[1,0]
	v_exp_f32_e32 v218, v218
	v_exp_f32_e32 v224, v224
	v_exp_f32_e32 v219, v219
	v_exp_f32_e32 v225, v225
	v_pk_add_f32 v[218:219], v[218:219], 1.0 op_sel_hi:[1,0]
	v_pk_add_f32 v[224:225], v[224:225], 1.0 op_sel_hi:[1,0]
	v_rcp_f32_e32 v218, v218
	v_rcp_f32_e32 v224, v224
	v_rcp_f32_e32 v219, v219
	v_rcp_f32_e32 v225, v225
	v_pk_mul_f32 v[214:215], v[214:215], v[218:219]
	v_pk_mul_f32 v[220:221], v[220:221], v[224:225]
	v_pk_mul_f32 v[214:215], v[216:217], v[214:215]
	v_pk_mul_f32 v[220:221], v[222:223], v[220:221]
	v_cvt_pk_bf16_f32 v128, v214, v215
	v_cvt_pk_bf16_f32 v129, v220, v221
	global_store_dwordx4 v[210:211], v[126:129], off
	v_lshl_add_u64 v[210:211], v[210:211], 0, s[98:99]
	v_pk_fma_f32 v[214:215], v[10:11], v[146:147], v[154:155]
	v_pk_fma_f32 v[220:221], v[12:13], v[148:149], v[156:157]
	v_pk_fma_f32 v[216:217], v[14:15], v[150:151], v[158:159]
	v_pk_fma_f32 v[222:223], v[16:17], v[152:153], v[160:161]
	v_pk_fma_f32 v[214:215], v[138:139], v[2:3], v[214:215]
	v_pk_fma_f32 v[220:221], v[140:141], v[4:5], v[220:221]
	v_pk_fma_f32 v[216:217], v[142:143], v[6:7], v[216:217]
	v_pk_fma_f32 v[222:223], v[144:145], v[8:9], v[222:223]
	v_pk_fma_f32 v[214:215], v[130:131], v[18:19], v[214:215]
	v_pk_fma_f32 v[220:221], v[132:133], v[20:21], v[220:221]
	v_pk_fma_f32 v[216:217], v[134:135], v[22:23], v[216:217]
	v_pk_fma_f32 v[222:223], v[136:137], v[24:25], v[222:223]
	v_pk_mul_f32 v[218:219], v[214:215], s[88:89] op_sel_hi:[1,0]
	v_pk_mul_f32 v[224:225], v[220:221], s[88:89] op_sel_hi:[1,0]
	v_exp_f32_e32 v218, v218
	v_exp_f32_e32 v224, v224
	v_exp_f32_e32 v219, v219
	v_exp_f32_e32 v225, v225
	v_pk_add_f32 v[218:219], v[218:219], 1.0 op_sel_hi:[1,0]
	v_pk_add_f32 v[224:225], v[224:225], 1.0 op_sel_hi:[1,0]
	v_rcp_f32_e32 v218, v218
	v_rcp_f32_e32 v224, v224
	v_rcp_f32_e32 v219, v219
	v_rcp_f32_e32 v225, v225
	v_pk_mul_f32 v[214:215], v[214:215], v[218:219]
	v_pk_mul_f32 v[220:221], v[220:221], v[224:225]
	v_pk_mul_f32 v[214:215], v[216:217], v[214:215]
	v_pk_mul_f32 v[220:221], v[222:223], v[220:221]
	v_cvt_pk_bf16_f32 v104, v214, v215
	v_cvt_pk_bf16_f32 v105, v220, v221
	global_store_dwordx4 v[210:211], v[102:105], off
	s_andn2_b64 vcc, exec, s[42:43]
	s_cbranch_vccnz .LBB0_747
	s_and_b64 s[8:9], s[6:7], exec
	s_cselect_b32 s8, 0, 0x1000
	s_add_i32 s8, s8, 0
	v_lshl_add_u32 v0, v208, 2, s8
	v_add_u32_e32 v0, 0x22100, v0
	s_waitcnt vmcnt(8)
	ds_write_b64 v0, v[192:193]
